# v27: v25 + write-through (sc1) stores for the final normalised output
# speedup vs baseline: 1.0010x; 1.0010x over previous
; __device__ __forceinline__ float bperm(float v, int srclane) { return __int_as_float(__builtin_amdgcn_ds_bpermute(srclane << 2, __float_as_int(v))); }
; __device__ __forceinline__ float bperm(float v, int srclane) { return __int_as_float(__builtin_amdgcn_ds_bpermute(srclane << 2, __float_as_int(v))); }
; __device__ __forceinline__ void phase_final(float* x, const float* g, int gw, int NGW, int lane) {
;     ...
;     for (int r0 = gw; r0 < M; r0 += 4 * NGW) { f32x4 v[4][4]; float s[4];
; #pragma unroll
;         for (int q = 0; q < 4; ++q) { const int r = (r0 + q * NGW < M) ? r0 + q * NGW : r0; const f32x4* xr = (const f32x4*)(x + (size_t)r * D) + lane; s[q] = 0.f;
; #pragma unroll
;             for (int j = 0; j < 4; ++j) { v[q][j] = xr[64 * j]; s[q] += (v[q][j].x * v[q][j].x + v[q][j].y * v[q][j].y) + (v[q][j].z * v[q][j].z + v[q][j].w * v[q][j].w); } }
; #pragma unroll
;         for (int o = 1; o < 64; o <<= 1) {
; #pragma unroll
;             for (int q = 0; q < 4; ++q) s[q] += bperm(s[q], lane ^ o); }
.LBB0_1602:
	s_ashr_i32 s11, s10, 31
	s_lshl_b64 s[0:1], s[10:11], 12
	v_lshl_add_u64 v[82:83], v[80:81], 0, s[0:1]
	s_waitcnt lgkmcnt(2)
	global_load_dwordx4 v[20:23], v[82:83], off nt
	global_load_dwordx4 v[24:27], v[82:83], off offset:1024 nt
	s_waitcnt lgkmcnt(0)
	global_load_dwordx4 v[16:19], v[82:83], off offset:3072 nt
	global_load_dwordx4 v[28:31], v[82:83], off offset:2048 nt
	s_add_i32 s0, s10, s8
	s_cmpk_lt_i32 s0, 0x4000
	s_cselect_b32 s2, s0, s10
	s_ashr_i32 s3, s2, 31
	s_lshl_b64 s[2:3], s[2:3], 12
	s_add_i32 s6, s9, s10
	s_cmpk_lt_i32 s6, 0x4000
	v_lshl_add_u64 v[32:33], v[80:81], 0, s[2:3]
	s_cselect_b64 s[12:13], -1, 0
	global_load_dwordx4 v[60:63], v[32:33], off nt
	global_load_dwordx4 v[52:55], v[32:33], off offset:1024 nt
	global_load_dwordx4 v[76:79], v[32:33], off offset:2048 nt
	global_load_dwordx4 v[72:75], v[32:33], off offset:3072 nt
	s_and_b64 s[2:3], s[12:13], exec
	s_cselect_b32 s2, s6, s10
	s_ashr_i32 s3, s2, 31
	s_lshl_b64 s[2:3], s[2:3], 12
	v_lshl_add_u64 v[32:33], v[80:81], 0, s[2:3]
	global_load_dwordx4 v[68:71], v[32:33], off nt
	global_load_dwordx4 v[64:67], v[32:33], off offset:1024 nt
	global_load_dwordx4 v[56:59], v[32:33], off offset:2048 nt
	global_load_dwordx4 v[48:51], v[32:33], off offset:3072 nt
	s_add_i32 s2, s14, s10
	s_cmpk_lt_i32 s2, 0x4000
	s_cselect_b64 s[4:5], -1, 0
	s_and_b64 s[16:17], s[4:5], exec
	s_cselect_b32 s10, s2, s10
	s_ashr_i32 s11, s10, 31
	s_lshl_b64 s[10:11], s[10:11], 12
	v_lshl_add_u64 v[92:93], v[80:81], 0, s[10:11]
	global_load_dwordx4 v[44:47], v[92:93], off nt
	global_load_dwordx4 v[40:43], v[92:93], off offset:1024 nt
	global_load_dwordx4 v[36:39], v[92:93], off offset:2048 nt
	global_load_dwordx4 v[32:35], v[92:93], off offset:3072 nt
	s_cmpk_gt_i32 s0, 0x3fff
	s_waitcnt vmcnt(15)
	v_pk_mul_f32 v[92:93], v[22:23], v[22:23]
	v_pk_mul_f32 v[94:95], v[20:21], v[20:21]
	s_waitcnt vmcnt(14)
	v_pk_mul_f32 v[96:97], v[26:27], v[26:27]
	v_pk_mul_f32 v[98:99], v[24:25], v[24:25]
	v_pk_mov_b32 v[104:105], v[94:95], v[92:93] op_sel:[1,0]
	v_mov_b32_e32 v95, v93
	v_pk_mov_b32 v[92:93], v[98:99], v[96:97] op_sel:[1,0]
	v_mov_b32_e32 v99, v97
	s_waitcnt vmcnt(13)
	v_mul_f32_e32 v103, v17, v17
	s_waitcnt vmcnt(12)
	v_mul_f32_e32 v100, v29, v29
	v_mul_f32_e32 v102, v31, v31
	v_pk_add_f32 v[94:95], v[104:105], v[94:95]
	v_pk_add_f32 v[92:93], v[92:93], v[98:99]
	v_mul_f32_e32 v91, v16, v16
	v_mul_f32_e32 v106, v18, v18
	v_mul_f32_e32 v107, v19, v19
	v_pk_fma_f32 v[96:97], v[28:29], v[28:29], v[100:101] op_sel_hi:[1,1,0]
	v_pk_fma_f32 v[100:101], v[30:31], v[30:31], v[102:103] op_sel_hi:[1,1,0]
	v_pk_add_f32 v[94:95], v[94:95], v[94:95] op_sel:[0,1] op_sel_hi:[1,0]
	v_pk_add_f32 v[92:93], v[92:93], v[92:93] op_sel:[0,1] op_sel_hi:[1,0]
	v_mov_b32_e32 v97, v106
	v_mov_b32_e32 v101, v107
	v_mov_b32_e32 v95, v91
	v_mov_b32_e32 v93, v103
	v_pk_add_f32 v[96:97], v[96:97], v[100:101]
	v_pk_add_f32 v[92:93], v[94:95], v[92:93]
	s_waitcnt vmcnt(11)
	v_mul_f32_e32 v91, v61, v61
	v_pk_add_f32 v[92:93], v[92:93], v[96:97]
	v_mul_f32_e32 v98, v63, v63
	v_add_f32_e32 v92, v92, v93
	ds_bpermute_b32 v93, v84, v92
	s_waitcnt vmcnt(10)
	v_mul_f32_e32 v99, v53, v53
	v_mul_f32_e32 v100, v55, v55
	s_waitcnt vmcnt(9)
	v_mul_f32_e32 v101, v77, v77
	v_mul_f32_e32 v102, v79, v79
	s_waitcnt lgkmcnt(0)
	v_add_f32_e32 v92, v92, v93
	ds_bpermute_b32 v93, v85, v92
	v_fmac_f32_e32 v91, v60, v60
	v_fmac_f32_e32 v98, v62, v62
	v_fmac_f32_e32 v99, v52, v52
	v_fmac_f32_e32 v100, v54, v54
	s_waitcnt lgkmcnt(0)
	v_add_f32_e32 v92, v92, v93
	ds_bpermute_b32 v93, v86, v92
	s_waitcnt vmcnt(8)
	v_mul_f32_e32 v103, v73, v73
	v_mul_f32_e32 v104, v75, v75
	v_fmac_f32_e32 v101, v76, v76
	v_fmac_f32_e32 v102, v78, v78
	s_waitcnt lgkmcnt(0)
	v_add_f32_e32 v92, v92, v93
	ds_bpermute_b32 v93, v87, v92
	v_add_f32_e32 v91, v91, v98
	v_add_f32_e32 v94, v99, v100
	v_fmac_f32_e32 v103, v72, v72
	v_fmac_f32_e32 v104, v74, v74
	s_waitcnt lgkmcnt(0)
	v_add_f32_e32 v92, v92, v93
	ds_bpermute_b32 v93, v88, v92
	v_add_f32_e32 v95, v101, v102
	v_add_f32_e32 v91, v91, v94
	v_add_f32_e32 v96, v103, v104
	v_add_f32_e32 v91, v91, v95
	s_waitcnt lgkmcnt(0)
	v_add_f32_e32 v92, v92, v93
	ds_bpermute_b32 v93, v89, v92
	v_add_f32_e32 v91, v91, v96
	s_waitcnt vmcnt(7)
; __device__ __forceinline__ float bperm(float v, int srclane) { return __int_as_float(__builtin_amdgcn_ds_bpermute(srclane << 2, __float_as_int(v))); }
; __device__ __forceinline__ float bperm(float v, int srclane) { return __int_as_float(__builtin_amdgcn_ds_bpermute(srclane << 2, __float_as_int(v))); }
; __device__ __forceinline__ void phase_final(float* x, const float* g, int gw, int NGW, int lane) {
;     ...
;     for (int r0 = gw; r0 < M; r0 += 4 * NGW) { f32x4 v[4][4]; float s[4];
; #pragma unroll
;         for (int q = 0; q < 4; ++q) { const int r = (r0 + q * NGW < M) ? r0 + q * NGW : r0; const f32x4* xr = (const f32x4*)(x + (size_t)r * D) + lane; s[q] = 0.f;
; #pragma unroll
;             for (int j = 0; j < 4; ++j) { v[q][j] = xr[64 * j]; s[q] += (v[q][j].x * v[q][j].x + v[q][j].y * v[q][j].y) + (v[q][j].z * v[q][j].z + v[q][j].w * v[q][j].w); } }
; #pragma unroll
;         for (int o = 1; o < 64; o <<= 1) {
; #pragma unroll
;             for (int q = 0; q < 4; ++q) s[q] += bperm(s[q], lane ^ o); }
; #pragma unroll
;         for (int q = 0; q < 4; ++q) { const int r = r0 + q * NGW; if (r < M) { const float rs = rsqrtf(s[q] * (1.f / D) + 1e-6f); f32x4* xr = (f32x4*)(x + (size_t)r * D) + lane;
; #pragma unroll
;                 for (int j = 0; j < 4; ++j) xr[64 * j] = (f32x4){v[q][j].x * rs * gv[j].x, v[q][j].y * rs * gv[j].y, v[q][j].z * rs * gv[j].z, v[q][j].w * rs * gv[j].w}; } }
	v_mul_f32_e32 v94, v69, v69
	v_mul_f32_e32 v95, v71, v71
	s_waitcnt vmcnt(6)
	v_mul_f32_e32 v96, v65, v65
	s_waitcnt lgkmcnt(0)
	v_add_f32_e32 v92, v92, v93
	v_fmamk_f32 v92, v92, 0x3a800000, v90
	v_mul_f32_e32 v93, 0x4b800000, v92
	v_cmp_gt_f32_e32 vcc, s15, v92
	v_mul_f32_e32 v97, v67, v67
	s_waitcnt vmcnt(5)
	v_mul_f32_e32 v98, v57, v57
	v_cndmask_b32_e32 v92, v92, v93, vcc
	v_rsq_f32_e32 v92, v92
	v_mul_f32_e32 v99, v59, v59
	v_fmac_f32_e32 v94, v68, v68
	v_fmac_f32_e32 v95, v70, v70
	v_fmac_f32_e32 v96, v64, v64
	v_fmac_f32_e32 v97, v66, v66
	v_fmac_f32_e32 v98, v56, v56
	v_fmac_f32_e32 v99, v58, v58
	v_add_f32_e32 v94, v94, v95
	v_add_f32_e32 v95, v96, v97
	v_add_f32_e32 v93, v98, v99
	v_add_f32_e32 v94, v94, v95
	v_add_f32_e32 v93, v94, v93
	v_mul_f32_e32 v94, 0x45800000, v92
	v_cndmask_b32_e32 v92, v92, v94, vcc
	s_waitcnt vmcnt(4)
	v_mul_f32_e32 v100, v49, v49
	v_pk_mul_f32 v[94:95], v[16:17], v[92:93] op_sel_hi:[1,0]
	v_mul_f32_e32 v16, v51, v51
	v_fmac_f32_e32 v100, v48, v48
	v_fmac_f32_e32 v16, v50, v50
	v_add_f32_e32 v16, v100, v16
	v_pk_mul_f32 v[20:21], v[20:21], v[92:93] op_sel_hi:[1,0]
	v_pk_mul_f32 v[22:23], v[22:23], v[92:93] op_sel_hi:[1,0]
	v_pk_mul_f32 v[24:25], v[24:25], v[92:93] op_sel_hi:[1,0]
	v_pk_mul_f32 v[26:27], v[26:27], v[92:93] op_sel_hi:[1,0]
	v_pk_mul_f32 v[28:29], v[28:29], v[92:93] op_sel_hi:[1,0]
	v_pk_mul_f32 v[30:31], v[30:31], v[92:93] op_sel_hi:[1,0]
	v_add_f32_e32 v16, v93, v16
	s_waitcnt vmcnt(3)
	v_mul_f32_e32 v17, v45, v45
	v_mul_f32_e32 v93, v47, v47
	v_fmac_f32_e32 v17, v44, v44
	v_fmac_f32_e32 v93, v46, v46
	v_add_f32_e32 v17, v17, v93
	s_waitcnt vmcnt(2)
	v_mul_f32_e32 v93, v41, v41
	v_mul_f32_e32 v96, v43, v43
	v_fmac_f32_e32 v93, v40, v40
	v_fmac_f32_e32 v96, v42, v42
	v_add_f32_e32 v93, v93, v96
	v_add_f32_e32 v17, v17, v93
	s_waitcnt vmcnt(1)
	v_mul_f32_e32 v93, v37, v37
	v_mul_f32_e32 v96, v39, v39
	v_fmac_f32_e32 v93, v36, v36
	v_fmac_f32_e32 v96, v38, v38
	v_add_f32_e32 v93, v93, v96
	v_add_f32_e32 v17, v17, v93
	s_waitcnt vmcnt(0)
	v_mul_f32_e32 v93, v33, v33
	v_mul_f32_e32 v96, v35, v35
	v_fmac_f32_e32 v93, v32, v32
	v_fmac_f32_e32 v96, v34, v34
	v_add_f32_e32 v93, v93, v96
	v_add_f32_e32 v17, v17, v93
	ds_bpermute_b32 v96, v84, v91
	ds_bpermute_b32 v97, v84, v16
	ds_bpermute_b32 v98, v84, v17
	v_pk_mul_f32 v[92:93], v[18:19], v[92:93] op_sel_hi:[1,0]
	v_pk_mul_f32 v[18:19], v[14:15], v[22:23]
	s_waitcnt lgkmcnt(2)
	v_add_f32_e32 v22, v91, v96
	s_waitcnt lgkmcnt(1)
	v_add_f32_e32 v23, v16, v97
	s_waitcnt lgkmcnt(0)
	v_add_f32_e32 v91, v17, v98
	ds_bpermute_b32 v96, v85, v22
	ds_bpermute_b32 v97, v85, v23
	ds_bpermute_b32 v98, v85, v91
	v_pk_mul_f32 v[16:17], v[12:13], v[20:21]
	global_store_dwordx4 v[82:83], v[16:19], off sc1
	s_waitcnt lgkmcnt(2)
	v_add_f32_e32 v20, v22, v96
	s_waitcnt lgkmcnt(1)
	v_add_f32_e32 v21, v23, v97
	s_waitcnt lgkmcnt(0)
	v_add_f32_e32 v22, v91, v98
	ds_bpermute_b32 v23, v86, v20
	ds_bpermute_b32 v91, v86, v21
	ds_bpermute_b32 v96, v86, v22
	v_pk_mul_f32 v[16:17], v[8:9], v[24:25]
	v_pk_mul_f32 v[18:19], v[10:11], v[26:27]
	s_waitcnt lgkmcnt(2)
	v_add_f32_e32 v20, v20, v23
	s_waitcnt lgkmcnt(1)
	v_add_f32_e32 v21, v21, v91
	s_waitcnt lgkmcnt(0)
	v_add_f32_e32 v22, v22, v96
	ds_bpermute_b32 v23, v87, v20
	ds_bpermute_b32 v24, v87, v21
	ds_bpermute_b32 v25, v87, v22
	global_store_dwordx4 v[82:83], v[16:19], off offset:1024 sc1
	s_waitcnt lgkmcnt(2)
	v_add_f32_e32 v20, v20, v23
	s_waitcnt lgkmcnt(1)
	v_add_f32_e32 v21, v21, v24
	s_waitcnt lgkmcnt(0)
	v_add_f32_e32 v22, v22, v25
	ds_bpermute_b32 v23, v88, v20
	ds_bpermute_b32 v24, v88, v21
	ds_bpermute_b32 v25, v88, v22
	v_pk_mul_f32 v[18:19], v[6:7], v[30:31]
	v_pk_mul_f32 v[16:17], v[4:5], v[28:29]
	global_store_dwordx4 v[82:83], v[16:19], off offset:2048 sc1
	s_waitcnt lgkmcnt(2)
	v_add_f32_e32 v20, v20, v23
	s_waitcnt lgkmcnt(1)
	v_add_f32_e32 v18, v21, v24
	s_waitcnt lgkmcnt(0)
	v_add_f32_e32 v16, v22, v25
	ds_bpermute_b32 v21, v89, v20
	ds_bpermute_b32 v19, v89, v18
	ds_bpermute_b32 v17, v89, v16
	v_pk_mul_f32 v[24:25], v[2:3], v[92:93]
	v_pk_mul_f32 v[22:23], v[0:1], v[94:95]
	global_store_dwordx4 v[82:83], v[22:25], off offset:3072 sc1
	s_cbranch_scc0 .LBB0_1605
	s_andn2_b64 vcc, exec, s[12:13]
	s_cbranch_vccz .LBB0_1606

; __device__ __forceinline__ void phase_final(float* x, const float* g, int gw, int NGW, int lane) {
;     ...
;         for (int q = 0; q < 4; ++q) { const int r = r0 + q * NGW; if (r < M) { const float rs = rsqrtf(s[q] * (1.f / D) + 1e-6f); f32x4* xr = (f32x4*)(x + (size_t)r * D) + lane;
; #pragma unroll
;                 for (int j = 0; j < 4; ++j) xr[64 * j] = (f32x4){v[q][j].x * rs * gv[j].x, v[q][j].y * rs * gv[j].y, v[q][j].z * rs * gv[j].z, v[q][j].w * rs * gv[j].w}; } }
.LBB0_1605:
	s_waitcnt lgkmcnt(2)
	v_add_f32_e32 v20, v20, v21
	v_fmamk_f32 v20, v20, 0x3a800000, v90
	v_mul_f32_e32 v21, 0x4b800000, v20
	v_cmp_gt_f32_e32 vcc, s15, v20
	s_ashr_i32 s1, s0, 31
	s_lshl_b64 s[10:11], s[0:1], 12
	v_cndmask_b32_e32 v20, v20, v21, vcc
	v_rsq_f32_e32 v20, v20
	v_lshl_add_u64 v[26:27], v[80:81], 0, s[10:11]
	v_mul_f32_e32 v21, 0x45800000, v20
	v_cndmask_b32_e32 v24, v20, v21, vcc
	v_pk_mul_f32 v[20:21], v[60:61], v[24:25] op_sel_hi:[1,0]
	v_pk_mul_f32 v[22:23], v[62:63], v[24:25] op_sel_hi:[1,0]
	v_pk_mul_f32 v[20:21], v[12:13], v[20:21]
	v_pk_mul_f32 v[22:23], v[14:15], v[22:23]
	global_store_dwordx4 v[26:27], v[20:23], off sc1
	s_nop 1
	v_pk_mul_f32 v[20:21], v[52:53], v[24:25] op_sel_hi:[1,0]
	v_pk_mul_f32 v[22:23], v[54:55], v[24:25] op_sel_hi:[1,0]
	v_pk_mul_f32 v[20:21], v[8:9], v[20:21]
	v_pk_mul_f32 v[22:23], v[10:11], v[22:23]
	global_store_dwordx4 v[26:27], v[20:23], off offset:1024 sc1
	s_nop 1
	v_pk_mul_f32 v[20:21], v[76:77], v[24:25] op_sel_hi:[1,0]
	v_pk_mul_f32 v[22:23], v[78:79], v[24:25] op_sel_hi:[1,0]
	v_pk_mul_f32 v[20:21], v[4:5], v[20:21]
	v_pk_mul_f32 v[22:23], v[6:7], v[22:23]
	global_store_dwordx4 v[26:27], v[20:23], off offset:2048 sc1
	s_nop 1
	v_pk_mul_f32 v[20:21], v[72:73], v[24:25] op_sel_hi:[1,0]
	v_pk_mul_f32 v[22:23], v[74:75], v[24:25] op_sel_hi:[1,0]
	v_pk_mul_f32 v[20:21], v[0:1], v[20:21]
	v_pk_mul_f32 v[22:23], v[2:3], v[22:23]
	global_store_dwordx4 v[26:27], v[20:23], off offset:3072 sc1
	s_andn2_b64 vcc, exec, s[12:13]
	s_cbranch_vccnz .LBB0_1604
.LBB0_1606:
	s_waitcnt lgkmcnt(1)
	v_add_f32_e32 v18, v18, v19
	v_fmamk_f32 v18, v18, 0x3a800000, v90
	v_mul_f32_e32 v19, 0x4b800000, v18
	v_cmp_gt_f32_e32 vcc, s15, v18
	s_ashr_i32 s7, s6, 31
	s_lshl_b64 s[6:7], s[6:7], 12
	v_cndmask_b32_e32 v18, v18, v19, vcc
	v_rsq_f32_e32 v18, v18
	v_lshl_add_u64 v[24:25], v[80:81], 0, s[6:7]
	v_mul_f32_e32 v19, 0x45800000, v18
	v_cndmask_b32_e32 v22, v18, v19, vcc
	v_pk_mul_f32 v[18:19], v[68:69], v[22:23] op_sel_hi:[1,0]
	v_pk_mul_f32 v[20:21], v[70:71], v[22:23] op_sel_hi:[1,0]
	v_pk_mul_f32 v[18:19], v[12:13], v[18:19]
	v_pk_mul_f32 v[20:21], v[14:15], v[20:21]
	global_store_dwordx4 v[24:25], v[18:21], off sc1
	s_nop 1
	v_pk_mul_f32 v[18:19], v[64:65], v[22:23] op_sel_hi:[1,0]
	v_pk_mul_f32 v[20:21], v[66:67], v[22:23] op_sel_hi:[1,0]
	v_pk_mul_f32 v[18:19], v[8:9], v[18:19]
	v_pk_mul_f32 v[20:21], v[10:11], v[20:21]
	global_store_dwordx4 v[24:25], v[18:21], off offset:1024 sc1
	s_nop 1
	v_pk_mul_f32 v[18:19], v[56:57], v[22:23] op_sel_hi:[1,0]
	v_pk_mul_f32 v[20:21], v[58:59], v[22:23] op_sel_hi:[1,0]
	v_pk_mul_f32 v[18:19], v[4:5], v[18:19]
	v_pk_mul_f32 v[20:21], v[6:7], v[20:21]
	global_store_dwordx4 v[24:25], v[18:21], off offset:2048 sc1
	s_nop 1
	v_pk_mul_f32 v[18:19], v[48:49], v[22:23] op_sel_hi:[1,0]
	v_pk_mul_f32 v[20:21], v[50:51], v[22:23] op_sel_hi:[1,0]
	v_pk_mul_f32 v[18:19], v[0:1], v[18:19]
	v_pk_mul_f32 v[20:21], v[2:3], v[20:21]
	global_store_dwordx4 v[24:25], v[18:21], off offset:3072 sc1
	s_andn2_b64 vcc, exec, s[4:5]
	s_cbranch_vccnz .LBB0_1601
.LBB0_1607:
	s_waitcnt lgkmcnt(0)
	v_add_f32_e32 v16, v16, v17
	v_fmamk_f32 v16, v16, 0x3a800000, v90
	v_mul_f32_e32 v17, 0x4b800000, v16
	v_cmp_gt_f32_e32 vcc, s15, v16
	s_ashr_i32 s3, s2, 31
	s_lshl_b64 s[2:3], s[2:3], 12
	v_cndmask_b32_e32 v16, v16, v17, vcc
	v_rsq_f32_e32 v16, v16
	v_lshl_add_u64 v[22:23], v[80:81], 0, s[2:3]
	v_mul_f32_e32 v17, 0x45800000, v16
	v_cndmask_b32_e32 v20, v16, v17, vcc
	v_pk_mul_f32 v[16:17], v[44:45], v[20:21] op_sel_hi:[1,0]
	v_pk_mul_f32 v[18:19], v[46:47], v[20:21] op_sel_hi:[1,0]
	v_pk_mul_f32 v[16:17], v[12:13], v[16:17]
	v_pk_mul_f32 v[18:19], v[14:15], v[18:19]
	global_store_dwordx4 v[22:23], v[16:19], off sc1
	s_nop 1
	v_pk_mul_f32 v[16:17], v[40:41], v[20:21] op_sel_hi:[1,0]
	v_pk_mul_f32 v[18:19], v[42:43], v[20:21] op_sel_hi:[1,0]
	v_pk_mul_f32 v[16:17], v[8:9], v[16:17]
	v_pk_mul_f32 v[18:19], v[10:11], v[18:19]
	global_store_dwordx4 v[22:23], v[16:19], off offset:1024 sc1
	s_nop 1
	v_pk_mul_f32 v[16:17], v[36:37], v[20:21] op_sel_hi:[1,0]
	v_pk_mul_f32 v[18:19], v[38:39], v[20:21] op_sel_hi:[1,0]
	v_pk_mul_f32 v[16:17], v[4:5], v[16:17]
	v_pk_mul_f32 v[18:19], v[6:7], v[18:19]
	global_store_dwordx4 v[22:23], v[16:19], off offset:2048 sc1
	s_nop 1
	v_pk_mul_f32 v[16:17], v[32:33], v[20:21] op_sel_hi:[1,0]
	v_pk_mul_f32 v[18:19], v[34:35], v[20:21] op_sel_hi:[1,0]
	v_pk_mul_f32 v[16:17], v[0:1], v[16:17]
	v_pk_mul_f32 v[18:19], v[2:3], v[18:19]
	global_store_dwordx4 v[22:23], v[16:19], off offset:3072 sc1
	s_branch .LBB0_1601
